# K loop: the vmcnt(8) and lgkmcnt(0) waits before each barrier merged into one s_waitcnt (one fewer instruction per load segment), on top of v45
# speedup vs baseline: 1.0042x; 1.0042x over previous
; #define PG8_STAGE(bufoff, gbase, voff) do { _Pragma("unroll") for (int _i = 0; _i < 2; ++_i) \
;         __builtin_amdgcn_global_load_lds((const unsigned*)((const char*)(gbase) + (voff)[_i]), (PG8_LAS unsigned*)(lds + (bufoff) + ldsw + _i * 8192), 16, 0, 0); } while (0)
; #define PG8_LDA(dst, b, h) do { _Pragma("unroll") for (int m = 0; m < 4; ++m) _Pragma("unroll") for (int k = 0; k < 2; ++k) dst[m][k] = *(const PG8_LAS bf16x8*)(lds + PG8_SA(b, h) + aoff + m * 2048 + k * 1024); } while (0)
; #define PG8_LDB(dst, b, h) do { _Pragma("unroll") for (int n = 0; n < 2; ++n) _Pragma("unroll") for (int k = 0; k < 2; ++k) dst[n][k] = *(const PG8_LAS bf16x8*)(lds + PG8_SB(b, h) + boff + n * 2048 + k * 1024); } while (0)
; #define PG8_MMA(ai, bj, At, Bt) do { __builtin_amdgcn_s_setprio(1); _Pragma("unroll") for (int m = 0; m < 4; ++m) _Pragma("unroll") for (int n = 0; n < 2; ++n) _Pragma("unroll") for (int k = 0; k < 2; ++k) \
;         acc[ai][bj][m][n] = __builtin_amdgcn_mfma_f32_16x16x32_bf16(Bt[n][k], At[m][k], acc[ai][bj][m][n], 0, 0, 0); __builtin_amdgcn_s_setprio(0); } while (0)
; #define PG8_WAIT_V(n) asm volatile("s_waitcnt vmcnt(" #n ")" ::: "memory")
; #define PG8_BAR __builtin_amdgcn_s_barrier()
; template <class Epi, class Sched, bool ALIGN_EPI = false, bool SP2 = false>
; __device__ __forceinline__ void gemm_phase(PG8_LAS unsigned char* lds, const Gemm g, const Sched& S, const Epi& E) {
;     ...
;         for (int t = 0; t < nt; t += 2) {
;             const bool last = (t == nt - 2);
;             const char* a1 = cA + (size_t)(t + 1) * kstep;
;             const char* a2 = last ? nA : cA + (size_t)(t + 2) * kstep; const char* b2 = last ? nB : cB + (size_t)(t + 2) * kstep;
;             const char* a3 = a2 + kstep; const char* b3 = b2 + kstep;
;             if (last && has_next) S.a_ready(nxt);
;             if constexpr (SP2) {
;             PG8_LDB(B0, 0, 0); PG8_LDB(B1, 0, 1); PG8_SCHED; PG8_LDA(At, 0, 0); PG8_STAGE(PG8_SA(1, 1), a1 + hstep, voffA);
;             PG8_WAIT_V(8); PG8_WAIT_L(0); PG8_BAR; PG8_MMA(0, 0, At, B0); PG8_MMA(0, 1, At, B1); PG8_BAR; PG8_SCHED;
;             PG8_LDA(At, 0, 1); PG8_STAGE(PG8_SB(0, 0), b2, voffB); PG8_STAGE(PG8_SB(0, 1), b2 + hstep, voffB); PG8_STAGE(PG8_SA(0, 0), a2, voffA);
;             PG8_WAIT_V(8); PG8_WAIT_L(0); PG8_BAR; PG8_MMA(1, 0, At, B0); PG8_MMA(1, 1, At, B1); PG8_BAR; PG8_SCHED;
.LBB0_321:
	s_add_u32 s12, s16, 0x80
	s_addc_u32 s13, s17, 0
	s_add_u32 s16, s14, 0x100
	s_addc_u32 s17, s15, 0
	s_mov_b32 s14, 0
	s_nop 0
	s_nop 0
	s_waitcnt lgkmcnt(0)
	s_add_i32 s42, s14, 2
	s_add_u32 s43, s12, 0x80
	s_addc_u32 s15, s13, 0
	s_add_i32 s75, 0, 0x10000
	s_cmp_eq_u32 s25, s14
	s_cselect_b32 s15, s55, s15
	s_cselect_b32 s14, s54, s43
	s_cselect_b32 vcc_hi, s65, s17
	s_cselect_b32 vcc_lo, s64, s16
	s_add_i32 s43, 0, 0x14000
	v_add_u32_e32 v142, s75, v199
	v_add_u32_e32 v178, s43, v199
	ds_read_b128 v[130:133], v142
	ds_read_b128 v[134:137], v142 offset:1024
	ds_read_b128 v[138:141], v142 offset:2048
	ds_read_b128 v[142:145], v142 offset:3072
	ds_read_b128 v[170:173], v178
	ds_read_b128 v[174:177], v178 offset:1024
	ds_read_b128 v[202:205], v178 offset:2048
	ds_read_b128 v[206:209], v178 offset:3072
	v_lshl_add_u64 v[178:179], s[12:13], 0, v[166:167]
	s_add_i32 m0, s56, 0xc000
	ds_read_b128 v[210:213], v201
	ds_read_b128 v[214:217], v201 offset:1024
	ds_read_b128 v[218:221], v201 offset:2048
	ds_read_b128 v[222:225], v201 offset:3072
	ds_read_b128 v[226:229], v201 offset:4096
	ds_read_b128 v[230:233], v201 offset:5120
	ds_read_b128 v[234:237], v201 offset:6144
	ds_read_b128 v[238:241], v201 offset:7168
	global_load_lds_dwordx4 v[178:179], off
	v_lshl_add_u64 v[178:179], s[12:13], 0, v[168:169]
	s_add_i32 m0, s56, 0xe000
	s_nop 0
	global_load_lds_dwordx4 v[178:179], off
	s_waitcnt vmcnt(8) lgkmcnt(0)
	s_setprio 1
	s_barrier
	v_mfma_f32_16x16x32_bf16 v[126:129], v[130:133], v[210:213], 0
	v_mfma_f32_16x16x32_bf16 v[126:129], v[134:137], v[214:217], v[126:129]
	v_mfma_f32_16x16x32_bf16 v[122:125], v[138:141], v[210:213], 0
	v_mfma_f32_16x16x32_bf16 v[122:125], v[142:145], v[214:217], v[122:125]
	v_mfma_f32_16x16x32_bf16 v[110:113], v[130:133], v[218:221], 0
	v_mfma_f32_16x16x32_bf16 v[110:113], v[134:137], v[222:225], v[110:113]
	v_mfma_f32_16x16x32_bf16 v[106:109], v[138:141], v[218:221], 0
	v_mfma_f32_16x16x32_bf16 v[106:109], v[142:145], v[222:225], v[106:109]
	v_mfma_f32_16x16x32_bf16 v[94:97], v[130:133], v[226:229], 0
	v_mfma_f32_16x16x32_bf16 v[94:97], v[134:137], v[230:233], v[94:97]
	v_mfma_f32_16x16x32_bf16 v[90:93], v[138:141], v[226:229], 0
	v_mfma_f32_16x16x32_bf16 v[90:93], v[142:145], v[230:233], v[90:93]
	v_mfma_f32_16x16x32_bf16 v[78:81], v[130:133], v[234:237], 0
	v_mfma_f32_16x16x32_bf16 v[78:81], v[134:137], v[238:241], v[78:81]
	v_mfma_f32_16x16x32_bf16 v[74:77], v[138:141], v[234:237], 0
	v_mfma_f32_16x16x32_bf16 v[74:77], v[142:145], v[238:241], v[74:77]
	v_mfma_f32_16x16x32_bf16 v[118:121], v[170:173], v[210:213], 0
	v_mfma_f32_16x16x32_bf16 v[118:121], v[174:177], v[214:217], v[118:121]
	v_mfma_f32_16x16x32_bf16 v[114:117], v[202:205], v[210:213], 0
	v_mfma_f32_16x16x32_bf16 v[114:117], v[206:209], v[214:217], v[114:117]
	v_mfma_f32_16x16x32_bf16 v[102:105], v[170:173], v[218:221], 0
	v_mfma_f32_16x16x32_bf16 v[102:105], v[174:177], v[222:225], v[102:105]
	v_mfma_f32_16x16x32_bf16 v[98:101], v[202:205], v[218:221], 0
	v_mfma_f32_16x16x32_bf16 v[98:101], v[206:209], v[222:225], v[98:101]
	v_mfma_f32_16x16x32_bf16 v[86:89], v[170:173], v[226:229], 0
	v_mfma_f32_16x16x32_bf16 v[86:89], v[174:177], v[230:233], v[86:89]
	v_mfma_f32_16x16x32_bf16 v[82:85], v[202:205], v[226:229], 0
	v_mfma_f32_16x16x32_bf16 v[82:85], v[206:209], v[230:233], v[82:85]
	v_mfma_f32_16x16x32_bf16 v[70:73], v[170:173], v[234:237], 0
	v_mfma_f32_16x16x32_bf16 v[70:73], v[174:177], v[238:241], v[70:73]
	v_mfma_f32_16x16x32_bf16 v[66:69], v[202:205], v[234:237], 0
	v_mfma_f32_16x16x32_bf16 v[66:69], v[206:209], v[238:241], v[66:69]
	s_barrier
	s_setprio 0
	s_add_i32 s75, s75, s23
	v_lshl_add_u64 v[178:179], vcc, 0, v[0:1]
	s_mov_b32 m0, s75
	ds_read_b128 v[210:213], v201 offset:16384
	ds_read_b128 v[214:217], v201 offset:17408
	ds_read_b128 v[218:221], v201 offset:18432
	ds_read_b128 v[222:225], v201 offset:19456
	ds_read_b128 v[226:229], v201 offset:20480
	ds_read_b128 v[230:233], v201 offset:21504
	ds_read_b128 v[234:237], v201 offset:22528
	ds_read_b128 v[238:241], v201 offset:23552
	global_load_lds_dwordx4 v[178:179], off
	s_add_i32 m0, s75, 0x2000
	v_lshl_add_u64 v[242:243], vcc, 0, v[162:163]
	s_add_u32 vcc_lo, vcc_lo, s84
	s_addc_u32 vcc_hi, vcc_hi, 0
	s_add_i32 s43, s43, s23
	global_load_lds_dwordx4 v[242:243], off
	v_lshl_add_u64 v[244:245], vcc, 0, v[0:1]
	s_mov_b32 m0, s43
	v_lshl_add_u64 v[246:247], vcc, 0, v[162:163]
	global_load_lds_dwordx4 v[244:245], off
	s_add_i32 m0, s43, 0x2000
	v_lshl_add_u64 v[248:249], s[14:15], 0, v[158:159]
	global_load_lds_dwordx4 v[246:247], off
	s_mov_b32 m0, s56
	v_lshl_add_u64 v[250:251], s[14:15], 0, v[160:161]
	global_load_lds_dwordx4 v[248:249], off
	s_mov_b32 m0, s82
	s_nop 0
	global_load_lds_dwordx4 v[250:251], off
	s_waitcnt vmcnt(8) lgkmcnt(0)
	s_setprio 1
	s_barrier
; #define PG8_STAGE(bufoff, gbase, voff) do { _Pragma("unroll") for (int _i = 0; _i < 2; ++_i) \
;         __builtin_amdgcn_global_load_lds((const unsigned*)((const char*)(gbase) + (voff)[_i]), (PG8_LAS unsigned*)(lds + (bufoff) + ldsw + _i * 8192), 16, 0, 0); } while (0)
; #define PG8_LDA(dst, b, h) do { _Pragma("unroll") for (int m = 0; m < 4; ++m) _Pragma("unroll") for (int k = 0; k < 2; ++k) dst[m][k] = *(const PG8_LAS bf16x8*)(lds + PG8_SA(b, h) + aoff + m * 2048 + k * 1024); } while (0)
; #define PG8_LDB(dst, b, h) do { _Pragma("unroll") for (int n = 0; n < 2; ++n) _Pragma("unroll") for (int k = 0; k < 2; ++k) dst[n][k] = *(const PG8_LAS bf16x8*)(lds + PG8_SB(b, h) + boff + n * 2048 + k * 1024); } while (0)
; #define PG8_MMA(ai, bj, At, Bt) do { __builtin_amdgcn_s_setprio(1); _Pragma("unroll") for (int m = 0; m < 4; ++m) _Pragma("unroll") for (int n = 0; n < 2; ++n) _Pragma("unroll") for (int k = 0; k < 2; ++k) \
;         acc[ai][bj][m][n] = __builtin_amdgcn_mfma_f32_16x16x32_bf16(Bt[n][k], At[m][k], acc[ai][bj][m][n], 0, 0, 0); __builtin_amdgcn_s_setprio(0); } while (0)
; #define PG8_WAIT_V(n) asm volatile("s_waitcnt vmcnt(" #n ")" ::: "memory")
; #define PG8_WAIT_L(n) asm volatile("s_waitcnt lgkmcnt(" #n ")" ::: "memory")
; #define PG8_BAR __builtin_amdgcn_s_barrier()
; #define PG8_SCHED __builtin_amdgcn_sched_barrier(0)
; template <class Epi, class Sched, bool ALIGN_EPI = false, bool SP2 = false>
; __device__ __forceinline__ void gemm_phase(PG8_LAS unsigned char* lds, const Gemm g, const Sched& S, const Epi& E) {
;     ...
;             PG8_WAIT_V(8); PG8_WAIT_L(0); PG8_BAR; PG8_MMA(1, 0, At, B0); PG8_MMA(1, 1, At, B1); PG8_BAR; PG8_SCHED;
;             PG8_LDB(B0, 1, 0); PG8_LDB(B1, 1, 1); PG8_SCHED; PG8_LDA(At, 1, 0); PG8_STAGE(PG8_SA(0, 1), a2 + hstep, voffA);
;             PG8_WAIT_V(8); PG8_WAIT_L(0); PG8_BAR; PG8_MMA(0, 0, At, B0); PG8_MMA(0, 1, At, B1); PG8_BAR; PG8_SCHED;
	v_mfma_f32_16x16x32_bf16 v[62:65], v[130:133], v[210:213], 0
	v_mfma_f32_16x16x32_bf16 v[62:65], v[134:137], v[214:217], v[62:65]
	v_mfma_f32_16x16x32_bf16 v[58:61], v[138:141], v[210:213], 0
	v_mfma_f32_16x16x32_bf16 v[58:61], v[142:145], v[214:217], v[58:61]
	v_mfma_f32_16x16x32_bf16 v[46:49], v[130:133], v[218:221], 0
	v_mfma_f32_16x16x32_bf16 v[46:49], v[134:137], v[222:225], v[46:49]
	v_mfma_f32_16x16x32_bf16 v[42:45], v[138:141], v[218:221], 0
	v_mfma_f32_16x16x32_bf16 v[42:45], v[142:145], v[222:225], v[42:45]
	v_mfma_f32_16x16x32_bf16 v[30:33], v[130:133], v[226:229], 0
	v_mfma_f32_16x16x32_bf16 v[30:33], v[134:137], v[230:233], v[30:33]
	v_mfma_f32_16x16x32_bf16 v[26:29], v[138:141], v[226:229], 0
	v_mfma_f32_16x16x32_bf16 v[26:29], v[142:145], v[230:233], v[26:29]
	v_mfma_f32_16x16x32_bf16 v[14:17], v[130:133], v[234:237], 0
	v_mfma_f32_16x16x32_bf16 v[14:17], v[134:137], v[238:241], v[14:17]
	v_mfma_f32_16x16x32_bf16 v[10:13], v[138:141], v[234:237], 0
	v_mfma_f32_16x16x32_bf16 v[10:13], v[142:145], v[238:241], v[10:13]
	v_mfma_f32_16x16x32_bf16 v[54:57], v[170:173], v[210:213], 0
	v_mfma_f32_16x16x32_bf16 v[54:57], v[174:177], v[214:217], v[54:57]
	v_mfma_f32_16x16x32_bf16 v[50:53], v[202:205], v[210:213], 0
	v_mfma_f32_16x16x32_bf16 v[50:53], v[206:209], v[214:217], v[50:53]
	v_mfma_f32_16x16x32_bf16 v[38:41], v[170:173], v[218:221], 0
	v_mfma_f32_16x16x32_bf16 v[38:41], v[174:177], v[222:225], v[38:41]
	v_mfma_f32_16x16x32_bf16 v[34:37], v[202:205], v[218:221], 0
	v_mfma_f32_16x16x32_bf16 v[34:37], v[206:209], v[222:225], v[34:37]
	v_mfma_f32_16x16x32_bf16 v[22:25], v[170:173], v[226:229], 0
	v_mfma_f32_16x16x32_bf16 v[22:25], v[174:177], v[230:233], v[22:25]
	v_mfma_f32_16x16x32_bf16 v[18:21], v[202:205], v[226:229], 0
	v_mfma_f32_16x16x32_bf16 v[18:21], v[206:209], v[230:233], v[18:21]
	v_mfma_f32_16x16x32_bf16 v[6:9], v[170:173], v[234:237], 0
	v_mfma_f32_16x16x32_bf16 v[6:9], v[174:177], v[238:241], v[6:9]
	v_mfma_f32_16x16x32_bf16 v[2:5], v[202:205], v[234:237], 0
	v_mfma_f32_16x16x32_bf16 v[2:5], v[206:209], v[238:241], v[2:5]
	s_barrier
	s_setprio 0
	s_add_i32 s43, 0, 0x18000
	s_add_i32 s75, 0, 0x1c000
	v_add_u32_e32 v142, s43, v199
	v_add_u32_e32 v206, s75, v199
	ds_read_b128 v[130:133], v142
	ds_read_b128 v[134:137], v142 offset:1024
	ds_read_b128 v[138:141], v142 offset:2048
	ds_read_b128 v[142:145], v142 offset:3072
	ds_read_b128 v[170:173], v206
	ds_read_b128 v[174:177], v206 offset:1024
	ds_read_b128 v[202:205], v206 offset:2048
	ds_read_b128 v[206:209], v206 offset:3072
	s_add_u32 s14, s14, s84
	s_addc_u32 s15, s15, 0
	s_mov_b32 m0, s83
	v_lshl_add_u64 v[252:253], s[14:15], 0, v[158:159]
	ds_read_b128 v[210:213], v201 offset:32768
	ds_read_b128 v[214:217], v201 offset:33792
	ds_read_b128 v[218:221], v201 offset:34816
	ds_read_b128 v[222:225], v201 offset:35840
	ds_read_b128 v[226:229], v201 offset:36864
	ds_read_b128 v[230:233], v201 offset:37888
	ds_read_b128 v[234:237], v201 offset:38912
	ds_read_b128 v[238:241], v201 offset:39936
	global_load_lds_dwordx4 v[252:253], off
	v_lshl_add_u64 v[252:253], s[14:15], 0, v[160:161]
	s_mov_b32 m0, s24
	s_nop 0
	global_load_lds_dwordx4 v[252:253], off
	s_waitcnt vmcnt(8) lgkmcnt(0)
	s_setprio 1
	s_barrier
	v_mfma_f32_16x16x32_bf16 v[126:129], v[130:133], v[210:213], v[126:129]
	v_mfma_f32_16x16x32_bf16 v[126:129], v[134:137], v[214:217], v[126:129]
	v_mfma_f32_16x16x32_bf16 v[122:125], v[138:141], v[210:213], v[122:125]
	v_mfma_f32_16x16x32_bf16 v[122:125], v[142:145], v[214:217], v[122:125]
	v_mfma_f32_16x16x32_bf16 v[110:113], v[130:133], v[218:221], v[110:113]
	v_mfma_f32_16x16x32_bf16 v[110:113], v[134:137], v[222:225], v[110:113]
	v_mfma_f32_16x16x32_bf16 v[106:109], v[138:141], v[218:221], v[106:109]
	v_mfma_f32_16x16x32_bf16 v[106:109], v[142:145], v[222:225], v[106:109]
	v_mfma_f32_16x16x32_bf16 v[94:97], v[130:133], v[226:229], v[94:97]
	v_mfma_f32_16x16x32_bf16 v[94:97], v[134:137], v[230:233], v[94:97]
	v_mfma_f32_16x16x32_bf16 v[90:93], v[138:141], v[226:229], v[90:93]
	v_mfma_f32_16x16x32_bf16 v[90:93], v[142:145], v[230:233], v[90:93]
	v_mfma_f32_16x16x32_bf16 v[78:81], v[130:133], v[234:237], v[78:81]
	v_mfma_f32_16x16x32_bf16 v[78:81], v[134:137], v[238:241], v[78:81]
	v_mfma_f32_16x16x32_bf16 v[74:77], v[138:141], v[234:237], v[74:77]
	v_mfma_f32_16x16x32_bf16 v[74:77], v[142:145], v[238:241], v[74:77]
	v_mfma_f32_16x16x32_bf16 v[118:121], v[170:173], v[210:213], v[118:121]
	v_mfma_f32_16x16x32_bf16 v[118:121], v[174:177], v[214:217], v[118:121]
	v_mfma_f32_16x16x32_bf16 v[114:117], v[202:205], v[210:213], v[114:117]
	v_mfma_f32_16x16x32_bf16 v[114:117], v[206:209], v[214:217], v[114:117]
	v_mfma_f32_16x16x32_bf16 v[102:105], v[170:173], v[218:221], v[102:105]
	v_mfma_f32_16x16x32_bf16 v[102:105], v[174:177], v[222:225], v[102:105]
	v_mfma_f32_16x16x32_bf16 v[98:101], v[202:205], v[218:221], v[98:101]
	v_mfma_f32_16x16x32_bf16 v[98:101], v[206:209], v[222:225], v[98:101]
	v_mfma_f32_16x16x32_bf16 v[86:89], v[170:173], v[226:229], v[86:89]
	v_mfma_f32_16x16x32_bf16 v[86:89], v[174:177], v[230:233], v[86:89]
	v_mfma_f32_16x16x32_bf16 v[82:85], v[202:205], v[226:229], v[82:85]
	v_mfma_f32_16x16x32_bf16 v[82:85], v[206:209], v[230:233], v[82:85]
	v_mfma_f32_16x16x32_bf16 v[70:73], v[170:173], v[234:237], v[70:73]
	v_mfma_f32_16x16x32_bf16 v[70:73], v[174:177], v[238:241], v[70:73]
	v_mfma_f32_16x16x32_bf16 v[66:69], v[202:205], v[234:237], v[66:69]
	v_mfma_f32_16x16x32_bf16 v[66:69], v[206:209], v[238:241], v[66:69]
	s_barrier
; #define PG8_STAGE(bufoff, gbase, voff) do { _Pragma("unroll") for (int _i = 0; _i < 2; ++_i) \
;         __builtin_amdgcn_global_load_lds((const unsigned*)((const char*)(gbase) + (voff)[_i]), (PG8_LAS unsigned*)(lds + (bufoff) + ldsw + _i * 8192), 16, 0, 0); } while (0)
; #define PG8_LDA(dst, b, h) do { _Pragma("unroll") for (int m = 0; m < 4; ++m) _Pragma("unroll") for (int k = 0; k < 2; ++k) dst[m][k] = *(const PG8_LAS bf16x8*)(lds + PG8_SA(b, h) + aoff + m * 2048 + k * 1024); } while (0)
; #define PG8_LDB(dst, b, h) do { _Pragma("unroll") for (int n = 0; n < 2; ++n) _Pragma("unroll") for (int k = 0; k < 2; ++k) dst[n][k] = *(const PG8_LAS bf16x8*)(lds + PG8_SB(b, h) + boff + n * 2048 + k * 1024); } while (0)
; #define PG8_MMA(ai, bj, At, Bt) do { __builtin_amdgcn_s_setprio(1); _Pragma("unroll") for (int m = 0; m < 4; ++m) _Pragma("unroll") for (int n = 0; n < 2; ++n) _Pragma("unroll") for (int k = 0; k < 2; ++k) \
;         acc[ai][bj][m][n] = __builtin_amdgcn_mfma_f32_16x16x32_bf16(Bt[n][k], At[m][k], acc[ai][bj][m][n], 0, 0, 0); __builtin_amdgcn_s_setprio(0); } while (0)
; #define PG8_WAIT_V(n) asm volatile("s_waitcnt vmcnt(" #n ")" ::: "memory")
; #define PG8_WAIT_L(n) asm volatile("s_waitcnt lgkmcnt(" #n ")" ::: "memory")
; #define PG8_BAR __builtin_amdgcn_s_barrier()
; #define PG8_SCHED __builtin_amdgcn_sched_barrier(0)
; template <class Epi, class Sched, bool ALIGN_EPI = false, bool SP2 = false>
; __device__ __forceinline__ void gemm_phase(PG8_LAS unsigned char* lds, const Gemm g, const Sched& S, const Epi& E) {
;     ...
;         for (int t = 0; t < nt; t += 2) {
;             const bool last = (t == nt - 2);
;             const char* a1 = cA + (size_t)(t + 1) * kstep;
;             const char* a2 = last ? nA : cA + (size_t)(t + 2) * kstep; const char* b2 = last ? nB : cB + (size_t)(t + 2) * kstep;
;             const char* a3 = a2 + kstep; const char* b3 = b2 + kstep;
;             if (last && has_next) S.a_ready(nxt);
;             if constexpr (SP2) {
;             PG8_LDB(B0, 0, 0); PG8_LDB(B1, 0, 1); PG8_SCHED; PG8_LDA(At, 0, 0); PG8_STAGE(PG8_SA(1, 1), a1 + hstep, voffA);
;     ...
;             PG8_LDA(At, 1, 1); PG8_STAGE(PG8_SB(1, 0), b3, voffB); PG8_STAGE(PG8_SB(1, 1), b3 + hstep, voffB); PG8_STAGE(PG8_SA(1, 0), a3, voffA);
;             PG8_WAIT_V(8); PG8_WAIT_L(0); PG8_BAR; PG8_MMA(1, 0, At, B0); PG8_MMA(1, 1, At, B1); PG8_BAR; PG8_SCHED;
	s_setprio 0
	s_add_i32 s14, s43, s23
	v_lshl_add_u64 v[178:179], v[178:179], 0, s[94:95]
	s_mov_b32 m0, s14
	ds_read_b128 v[210:213], v201 offset:49152
	ds_read_b128 v[214:217], v201 offset:50176
	ds_read_b128 v[218:221], v201 offset:51200
	ds_read_b128 v[222:225], v201 offset:52224
	ds_read_b128 v[226:229], v201 offset:53248
	ds_read_b128 v[230:233], v201 offset:54272
	ds_read_b128 v[234:237], v201 offset:55296
	ds_read_b128 v[238:241], v201 offset:56320
	global_load_lds_dwordx4 v[178:179], off
	v_lshl_add_u64 v[178:179], v[242:243], 0, s[94:95]
	s_add_i32 m0, s14, 0x2000
	s_add_i32 s14, s75, s23
	global_load_lds_dwordx4 v[178:179], off
	v_lshl_add_u64 v[178:179], v[244:245], 0, s[94:95]
	s_mov_b32 m0, s14
	s_nop 0
	global_load_lds_dwordx4 v[178:179], off
	v_lshl_add_u64 v[178:179], v[246:247], 0, s[94:95]
	s_add_i32 m0, s14, 0x2000
	s_nop 0
	global_load_lds_dwordx4 v[178:179], off
	v_lshl_add_u64 v[178:179], v[248:249], 0, s[94:95]
	s_mov_b32 m0, s63
	s_nop 0
	global_load_lds_dwordx4 v[178:179], off
	v_lshl_add_u64 v[178:179], v[250:251], 0, s[94:95]
	s_mov_b32 m0, s70
	s_nop 0
	global_load_lds_dwordx4 v[178:179], off
	s_waitcnt vmcnt(8) lgkmcnt(0)
	s_setprio 1
	s_barrier
	v_mfma_f32_16x16x32_bf16 v[62:65], v[130:133], v[210:213], v[62:65]
	v_mfma_f32_16x16x32_bf16 v[62:65], v[134:137], v[214:217], v[62:65]
	v_mfma_f32_16x16x32_bf16 v[58:61], v[138:141], v[210:213], v[58:61]
	v_mfma_f32_16x16x32_bf16 v[58:61], v[142:145], v[214:217], v[58:61]
	v_mfma_f32_16x16x32_bf16 v[46:49], v[130:133], v[218:221], v[46:49]
	v_mfma_f32_16x16x32_bf16 v[46:49], v[134:137], v[222:225], v[46:49]
	v_mfma_f32_16x16x32_bf16 v[42:45], v[138:141], v[218:221], v[42:45]
	v_mfma_f32_16x16x32_bf16 v[42:45], v[142:145], v[222:225], v[42:45]
	v_mfma_f32_16x16x32_bf16 v[30:33], v[130:133], v[226:229], v[30:33]
	v_mfma_f32_16x16x32_bf16 v[30:33], v[134:137], v[230:233], v[30:33]
	v_mfma_f32_16x16x32_bf16 v[26:29], v[138:141], v[226:229], v[26:29]
	v_mfma_f32_16x16x32_bf16 v[26:29], v[142:145], v[230:233], v[26:29]
	v_mfma_f32_16x16x32_bf16 v[14:17], v[130:133], v[234:237], v[14:17]
	v_mfma_f32_16x16x32_bf16 v[14:17], v[134:137], v[238:241], v[14:17]
	v_mfma_f32_16x16x32_bf16 v[10:13], v[138:141], v[234:237], v[10:13]
	v_mfma_f32_16x16x32_bf16 v[10:13], v[142:145], v[238:241], v[10:13]
	v_mfma_f32_16x16x32_bf16 v[54:57], v[170:173], v[210:213], v[54:57]
	v_mfma_f32_16x16x32_bf16 v[54:57], v[174:177], v[214:217], v[54:57]
	v_mfma_f32_16x16x32_bf16 v[50:53], v[202:205], v[210:213], v[50:53]
	v_mfma_f32_16x16x32_bf16 v[50:53], v[206:209], v[214:217], v[50:53]
	v_mfma_f32_16x16x32_bf16 v[38:41], v[170:173], v[218:221], v[38:41]
	v_mfma_f32_16x16x32_bf16 v[38:41], v[174:177], v[222:225], v[38:41]
	v_mfma_f32_16x16x32_bf16 v[34:37], v[202:205], v[218:221], v[34:37]
	v_mfma_f32_16x16x32_bf16 v[34:37], v[206:209], v[222:225], v[34:37]
	v_mfma_f32_16x16x32_bf16 v[22:25], v[170:173], v[226:229], v[22:25]
	v_mfma_f32_16x16x32_bf16 v[22:25], v[174:177], v[230:233], v[22:25]
	v_mfma_f32_16x16x32_bf16 v[18:21], v[202:205], v[226:229], v[18:21]
	v_mfma_f32_16x16x32_bf16 v[18:21], v[206:209], v[230:233], v[18:21]
	v_mfma_f32_16x16x32_bf16 v[6:9], v[170:173], v[234:237], v[6:9]
	v_mfma_f32_16x16x32_bf16 v[6:9], v[174:177], v[238:241], v[6:9]
	v_mfma_f32_16x16x32_bf16 v[2:5], v[202:205], v[234:237], v[2:5]
	v_mfma_f32_16x16x32_bf16 v[2:5], v[206:209], v[238:241], v[2:5]
	s_barrier
	s_setprio 0
	s_add_u32 s12, s12, 0x100
	s_addc_u32 s13, s13, 0
	s_add_u32 s16, s16, 0x100
	s_addc_u32 s17, s17, 0
	s_cmp_ge_u32 s42, s28
	s_mov_b32 s14, s42
	s_cbranch_scc0 .LBB0_322
	s_branch .Lk_done
.LBB0_322:
	s_add_i32 s42, s14, 2
	s_add_u32 s43, s12, 0x80
	s_addc_u32 s15, s13, 0
	s_add_i32 s75, 0, 0x10000
	s_cmp_eq_u32 s25, s14
	s_cselect_b32 s15, s55, s15
	s_cselect_b32 s14, s54, s43
	s_cselect_b32 vcc_hi, s65, s17
	s_cselect_b32 vcc_lo, s64, s16
	s_add_i32 s43, 0, 0x14000
	v_add_u32_e32 v142, s75, v199
	v_add_u32_e32 v178, s43, v199
	ds_read_b128 v[130:133], v142
	ds_read_b128 v[134:137], v142 offset:1024
	ds_read_b128 v[138:141], v142 offset:2048
	ds_read_b128 v[142:145], v142 offset:3072
	ds_read_b128 v[170:173], v178
	ds_read_b128 v[174:177], v178 offset:1024
	ds_read_b128 v[202:205], v178 offset:2048
	ds_read_b128 v[206:209], v178 offset:3072
	v_lshl_add_u64 v[178:179], s[12:13], 0, v[166:167]
	s_add_i32 m0, s56, 0xc000
	ds_read_b128 v[210:213], v201
	ds_read_b128 v[214:217], v201 offset:1024
	ds_read_b128 v[218:221], v201 offset:2048
	ds_read_b128 v[222:225], v201 offset:3072
	ds_read_b128 v[226:229], v201 offset:4096
	ds_read_b128 v[230:233], v201 offset:5120
	ds_read_b128 v[234:237], v201 offset:6144
	ds_read_b128 v[238:241], v201 offset:7168
	global_load_lds_dwordx4 v[178:179], off
	v_lshl_add_u64 v[178:179], s[12:13], 0, v[168:169]
	s_add_i32 m0, s56, 0xe000
	s_nop 0
	global_load_lds_dwordx4 v[178:179], off
	s_waitcnt vmcnt(8) lgkmcnt(0)
	s_setprio 1
	s_barrier
; #define PG8_STAGE(bufoff, gbase, voff) do { _Pragma("unroll") for (int _i = 0; _i < 2; ++_i) \
;         __builtin_amdgcn_global_load_lds((const unsigned*)((const char*)(gbase) + (voff)[_i]), (PG8_LAS unsigned*)(lds + (bufoff) + ldsw + _i * 8192), 16, 0, 0); } while (0)
; #define PG8_LDA(dst, b, h) do { _Pragma("unroll") for (int m = 0; m < 4; ++m) _Pragma("unroll") for (int k = 0; k < 2; ++k) dst[m][k] = *(const PG8_LAS bf16x8*)(lds + PG8_SA(b, h) + aoff + m * 2048 + k * 1024); } while (0)
; #define PG8_LDB(dst, b, h) do { _Pragma("unroll") for (int n = 0; n < 2; ++n) _Pragma("unroll") for (int k = 0; k < 2; ++k) dst[n][k] = *(const PG8_LAS bf16x8*)(lds + PG8_SB(b, h) + boff + n * 2048 + k * 1024); } while (0)
; #define PG8_MMA(ai, bj, At, Bt) do { __builtin_amdgcn_s_setprio(1); _Pragma("unroll") for (int m = 0; m < 4; ++m) _Pragma("unroll") for (int n = 0; n < 2; ++n) _Pragma("unroll") for (int k = 0; k < 2; ++k) \
;         acc[ai][bj][m][n] = __builtin_amdgcn_mfma_f32_16x16x32_bf16(Bt[n][k], At[m][k], acc[ai][bj][m][n], 0, 0, 0); __builtin_amdgcn_s_setprio(0); } while (0)
; #define PG8_WAIT_V(n) asm volatile("s_waitcnt vmcnt(" #n ")" ::: "memory")
; #define PG8_WAIT_L(n) asm volatile("s_waitcnt lgkmcnt(" #n ")" ::: "memory")
; #define PG8_BAR __builtin_amdgcn_s_barrier()
; #define PG8_SCHED __builtin_amdgcn_sched_barrier(0)
; template <class Epi, class Sched, bool ALIGN_EPI = false, bool SP2 = false>
; __device__ __forceinline__ void gemm_phase(PG8_LAS unsigned char* lds, const Gemm g, const Sched& S, const Epi& E) {
;     ...
;             PG8_LDB(B0, 0, 0); PG8_LDB(B1, 0, 1); PG8_SCHED; PG8_LDA(At, 0, 0); PG8_STAGE(PG8_SA(1, 1), a1 + hstep, voffA);
;             PG8_WAIT_V(8); PG8_WAIT_L(0); PG8_BAR; PG8_MMA(0, 0, At, B0); PG8_MMA(0, 1, At, B1); PG8_BAR; PG8_SCHED;
;             PG8_LDA(At, 0, 1); PG8_STAGE(PG8_SB(0, 0), b2, voffB); PG8_STAGE(PG8_SB(0, 1), b2 + hstep, voffB); PG8_STAGE(PG8_SA(0, 0), a2, voffA);
;             PG8_WAIT_V(8); PG8_WAIT_L(0); PG8_BAR; PG8_MMA(1, 0, At, B0); PG8_MMA(1, 1, At, B1); PG8_BAR; PG8_SCHED;
	v_mfma_f32_16x16x32_bf16 v[126:129], v[130:133], v[210:213], v[126:129]
	v_mfma_f32_16x16x32_bf16 v[126:129], v[134:137], v[214:217], v[126:129]
	v_mfma_f32_16x16x32_bf16 v[122:125], v[138:141], v[210:213], v[122:125]
	v_mfma_f32_16x16x32_bf16 v[122:125], v[142:145], v[214:217], v[122:125]
	v_mfma_f32_16x16x32_bf16 v[110:113], v[130:133], v[218:221], v[110:113]
	v_mfma_f32_16x16x32_bf16 v[110:113], v[134:137], v[222:225], v[110:113]
	v_mfma_f32_16x16x32_bf16 v[106:109], v[138:141], v[218:221], v[106:109]
	v_mfma_f32_16x16x32_bf16 v[106:109], v[142:145], v[222:225], v[106:109]
	v_mfma_f32_16x16x32_bf16 v[94:97], v[130:133], v[226:229], v[94:97]
	v_mfma_f32_16x16x32_bf16 v[94:97], v[134:137], v[230:233], v[94:97]
	v_mfma_f32_16x16x32_bf16 v[90:93], v[138:141], v[226:229], v[90:93]
	v_mfma_f32_16x16x32_bf16 v[90:93], v[142:145], v[230:233], v[90:93]
	v_mfma_f32_16x16x32_bf16 v[78:81], v[130:133], v[234:237], v[78:81]
	v_mfma_f32_16x16x32_bf16 v[78:81], v[134:137], v[238:241], v[78:81]
	v_mfma_f32_16x16x32_bf16 v[74:77], v[138:141], v[234:237], v[74:77]
	v_mfma_f32_16x16x32_bf16 v[74:77], v[142:145], v[238:241], v[74:77]
	v_mfma_f32_16x16x32_bf16 v[118:121], v[170:173], v[210:213], v[118:121]
	v_mfma_f32_16x16x32_bf16 v[118:121], v[174:177], v[214:217], v[118:121]
	v_mfma_f32_16x16x32_bf16 v[114:117], v[202:205], v[210:213], v[114:117]
	v_mfma_f32_16x16x32_bf16 v[114:117], v[206:209], v[214:217], v[114:117]
	v_mfma_f32_16x16x32_bf16 v[102:105], v[170:173], v[218:221], v[102:105]
	v_mfma_f32_16x16x32_bf16 v[102:105], v[174:177], v[222:225], v[102:105]
	v_mfma_f32_16x16x32_bf16 v[98:101], v[202:205], v[218:221], v[98:101]
	v_mfma_f32_16x16x32_bf16 v[98:101], v[206:209], v[222:225], v[98:101]
	v_mfma_f32_16x16x32_bf16 v[86:89], v[170:173], v[226:229], v[86:89]
	v_mfma_f32_16x16x32_bf16 v[86:89], v[174:177], v[230:233], v[86:89]
	v_mfma_f32_16x16x32_bf16 v[82:85], v[202:205], v[226:229], v[82:85]
	v_mfma_f32_16x16x32_bf16 v[82:85], v[206:209], v[230:233], v[82:85]
	v_mfma_f32_16x16x32_bf16 v[70:73], v[170:173], v[234:237], v[70:73]
	v_mfma_f32_16x16x32_bf16 v[70:73], v[174:177], v[238:241], v[70:73]
	v_mfma_f32_16x16x32_bf16 v[66:69], v[202:205], v[234:237], v[66:69]
	v_mfma_f32_16x16x32_bf16 v[66:69], v[206:209], v[238:241], v[66:69]
	s_barrier
	s_setprio 0
	s_add_i32 s75, s75, s23
	v_lshl_add_u64 v[178:179], vcc, 0, v[0:1]
	s_mov_b32 m0, s75
	ds_read_b128 v[210:213], v201 offset:16384
	ds_read_b128 v[214:217], v201 offset:17408
	ds_read_b128 v[218:221], v201 offset:18432
	ds_read_b128 v[222:225], v201 offset:19456
	ds_read_b128 v[226:229], v201 offset:20480
	ds_read_b128 v[230:233], v201 offset:21504
	ds_read_b128 v[234:237], v201 offset:22528
	ds_read_b128 v[238:241], v201 offset:23552
	global_load_lds_dwordx4 v[178:179], off
	s_add_i32 m0, s75, 0x2000
	v_lshl_add_u64 v[242:243], vcc, 0, v[162:163]
	s_add_u32 vcc_lo, vcc_lo, s84
	s_addc_u32 vcc_hi, vcc_hi, 0
	s_add_i32 s43, s43, s23
	global_load_lds_dwordx4 v[242:243], off
	v_lshl_add_u64 v[244:245], vcc, 0, v[0:1]
	s_mov_b32 m0, s43
	v_lshl_add_u64 v[246:247], vcc, 0, v[162:163]
	global_load_lds_dwordx4 v[244:245], off
	s_add_i32 m0, s43, 0x2000
	v_lshl_add_u64 v[248:249], s[14:15], 0, v[158:159]
	global_load_lds_dwordx4 v[246:247], off
	s_mov_b32 m0, s56
	v_lshl_add_u64 v[250:251], s[14:15], 0, v[160:161]
	global_load_lds_dwordx4 v[248:249], off
	s_mov_b32 m0, s82
	s_nop 0
	global_load_lds_dwordx4 v[250:251], off
	s_waitcnt vmcnt(8) lgkmcnt(0)
	s_setprio 1
	s_barrier
	v_mfma_f32_16x16x32_bf16 v[62:65], v[130:133], v[210:213], v[62:65]
	v_mfma_f32_16x16x32_bf16 v[62:65], v[134:137], v[214:217], v[62:65]
	v_mfma_f32_16x16x32_bf16 v[58:61], v[138:141], v[210:213], v[58:61]
	v_mfma_f32_16x16x32_bf16 v[58:61], v[142:145], v[214:217], v[58:61]
	v_mfma_f32_16x16x32_bf16 v[46:49], v[130:133], v[218:221], v[46:49]
	v_mfma_f32_16x16x32_bf16 v[46:49], v[134:137], v[222:225], v[46:49]
	v_mfma_f32_16x16x32_bf16 v[42:45], v[138:141], v[218:221], v[42:45]
	v_mfma_f32_16x16x32_bf16 v[42:45], v[142:145], v[222:225], v[42:45]
	v_mfma_f32_16x16x32_bf16 v[30:33], v[130:133], v[226:229], v[30:33]
	v_mfma_f32_16x16x32_bf16 v[30:33], v[134:137], v[230:233], v[30:33]
	v_mfma_f32_16x16x32_bf16 v[26:29], v[138:141], v[226:229], v[26:29]
	v_mfma_f32_16x16x32_bf16 v[26:29], v[142:145], v[230:233], v[26:29]
	v_mfma_f32_16x16x32_bf16 v[14:17], v[130:133], v[234:237], v[14:17]
	v_mfma_f32_16x16x32_bf16 v[14:17], v[134:137], v[238:241], v[14:17]
	v_mfma_f32_16x16x32_bf16 v[10:13], v[138:141], v[234:237], v[10:13]
	v_mfma_f32_16x16x32_bf16 v[10:13], v[142:145], v[238:241], v[10:13]
	v_mfma_f32_16x16x32_bf16 v[54:57], v[170:173], v[210:213], v[54:57]
	v_mfma_f32_16x16x32_bf16 v[54:57], v[174:177], v[214:217], v[54:57]
	v_mfma_f32_16x16x32_bf16 v[50:53], v[202:205], v[210:213], v[50:53]
	v_mfma_f32_16x16x32_bf16 v[50:53], v[206:209], v[214:217], v[50:53]
	v_mfma_f32_16x16x32_bf16 v[38:41], v[170:173], v[218:221], v[38:41]
	v_mfma_f32_16x16x32_bf16 v[38:41], v[174:177], v[222:225], v[38:41]
	v_mfma_f32_16x16x32_bf16 v[34:37], v[202:205], v[218:221], v[34:37]
	v_mfma_f32_16x16x32_bf16 v[34:37], v[206:209], v[222:225], v[34:37]
	v_mfma_f32_16x16x32_bf16 v[22:25], v[170:173], v[226:229], v[22:25]
	v_mfma_f32_16x16x32_bf16 v[22:25], v[174:177], v[230:233], v[22:25]
	v_mfma_f32_16x16x32_bf16 v[18:21], v[202:205], v[226:229], v[18:21]
	v_mfma_f32_16x16x32_bf16 v[18:21], v[206:209], v[230:233], v[18:21]
	v_mfma_f32_16x16x32_bf16 v[6:9], v[170:173], v[234:237], v[6:9]
	v_mfma_f32_16x16x32_bf16 v[6:9], v[174:177], v[238:241], v[6:9]
	v_mfma_f32_16x16x32_bf16 v[2:5], v[202:205], v[234:237], v[2:5]
	v_mfma_f32_16x16x32_bf16 v[2:5], v[206:209], v[238:241], v[2:5]
	s_barrier
; #define PG8_STAGE(bufoff, gbase, voff) do { _Pragma("unroll") for (int _i = 0; _i < 2; ++_i) \
;         __builtin_amdgcn_global_load_lds((const unsigned*)((const char*)(gbase) + (voff)[_i]), (PG8_LAS unsigned*)(lds + (bufoff) + ldsw + _i * 8192), 16, 0, 0); } while (0)
; #define PG8_LDA(dst, b, h) do { _Pragma("unroll") for (int m = 0; m < 4; ++m) _Pragma("unroll") for (int k = 0; k < 2; ++k) dst[m][k] = *(const PG8_LAS bf16x8*)(lds + PG8_SA(b, h) + aoff + m * 2048 + k * 1024); } while (0)
; #define PG8_LDB(dst, b, h) do { _Pragma("unroll") for (int n = 0; n < 2; ++n) _Pragma("unroll") for (int k = 0; k < 2; ++k) dst[n][k] = *(const PG8_LAS bf16x8*)(lds + PG8_SB(b, h) + boff + n * 2048 + k * 1024); } while (0)
; #define PG8_MMA(ai, bj, At, Bt) do { __builtin_amdgcn_s_setprio(1); _Pragma("unroll") for (int m = 0; m < 4; ++m) _Pragma("unroll") for (int n = 0; n < 2; ++n) _Pragma("unroll") for (int k = 0; k < 2; ++k) \
;         acc[ai][bj][m][n] = __builtin_amdgcn_mfma_f32_16x16x32_bf16(Bt[n][k], At[m][k], acc[ai][bj][m][n], 0, 0, 0); __builtin_amdgcn_s_setprio(0); } while (0)
; #define PG8_WAIT_V(n) asm volatile("s_waitcnt vmcnt(" #n ")" ::: "memory")
; #define PG8_WAIT_L(n) asm volatile("s_waitcnt lgkmcnt(" #n ")" ::: "memory")
; #define PG8_BAR __builtin_amdgcn_s_barrier()
; #define PG8_SCHED __builtin_amdgcn_sched_barrier(0)
; template <class Epi, class Sched, bool ALIGN_EPI = false, bool SP2 = false>
; __device__ __forceinline__ void gemm_phase(PG8_LAS unsigned char* lds, const Gemm g, const Sched& S, const Epi& E) {
;     ...
;             PG8_LDB(B0, 1, 0); PG8_LDB(B1, 1, 1); PG8_SCHED; PG8_LDA(At, 1, 0); PG8_STAGE(PG8_SA(0, 1), a2 + hstep, voffA);
;             PG8_WAIT_V(8); PG8_WAIT_L(0); PG8_BAR; PG8_MMA(0, 0, At, B0); PG8_MMA(0, 1, At, B1); PG8_BAR; PG8_SCHED;
;             PG8_LDA(At, 1, 1); PG8_STAGE(PG8_SB(1, 0), b3, voffB); PG8_STAGE(PG8_SB(1, 1), b3 + hstep, voffB); PG8_STAGE(PG8_SA(1, 0), a3, voffA);
;             PG8_WAIT_V(8); PG8_WAIT_L(0); PG8_BAR; PG8_MMA(1, 0, At, B0); PG8_MMA(1, 1, At, B1); PG8_BAR; PG8_SCHED;
	s_setprio 0
	s_add_i32 s43, 0, 0x18000
	s_add_i32 s75, 0, 0x1c000
	v_add_u32_e32 v142, s43, v199
	v_add_u32_e32 v206, s75, v199
	ds_read_b128 v[130:133], v142
	ds_read_b128 v[134:137], v142 offset:1024
	ds_read_b128 v[138:141], v142 offset:2048
	ds_read_b128 v[142:145], v142 offset:3072
	ds_read_b128 v[170:173], v206
	ds_read_b128 v[174:177], v206 offset:1024
	ds_read_b128 v[202:205], v206 offset:2048
	ds_read_b128 v[206:209], v206 offset:3072
	s_add_u32 s14, s14, s84
	s_addc_u32 s15, s15, 0
	s_mov_b32 m0, s83
	v_lshl_add_u64 v[252:253], s[14:15], 0, v[158:159]
	ds_read_b128 v[210:213], v201 offset:32768
	ds_read_b128 v[214:217], v201 offset:33792
	ds_read_b128 v[218:221], v201 offset:34816
	ds_read_b128 v[222:225], v201 offset:35840
	ds_read_b128 v[226:229], v201 offset:36864
	ds_read_b128 v[230:233], v201 offset:37888
	ds_read_b128 v[234:237], v201 offset:38912
	ds_read_b128 v[238:241], v201 offset:39936
	global_load_lds_dwordx4 v[252:253], off
	v_lshl_add_u64 v[252:253], s[14:15], 0, v[160:161]
	s_mov_b32 m0, s24
	s_nop 0
	global_load_lds_dwordx4 v[252:253], off
	s_waitcnt vmcnt(8) lgkmcnt(0)
	s_setprio 1
	s_barrier
	v_mfma_f32_16x16x32_bf16 v[126:129], v[130:133], v[210:213], v[126:129]
	v_mfma_f32_16x16x32_bf16 v[126:129], v[134:137], v[214:217], v[126:129]
	v_mfma_f32_16x16x32_bf16 v[122:125], v[138:141], v[210:213], v[122:125]
	v_mfma_f32_16x16x32_bf16 v[122:125], v[142:145], v[214:217], v[122:125]
	v_mfma_f32_16x16x32_bf16 v[110:113], v[130:133], v[218:221], v[110:113]
	v_mfma_f32_16x16x32_bf16 v[110:113], v[134:137], v[222:225], v[110:113]
	v_mfma_f32_16x16x32_bf16 v[106:109], v[138:141], v[218:221], v[106:109]
	v_mfma_f32_16x16x32_bf16 v[106:109], v[142:145], v[222:225], v[106:109]
	v_mfma_f32_16x16x32_bf16 v[94:97], v[130:133], v[226:229], v[94:97]
	v_mfma_f32_16x16x32_bf16 v[94:97], v[134:137], v[230:233], v[94:97]
	v_mfma_f32_16x16x32_bf16 v[90:93], v[138:141], v[226:229], v[90:93]
	v_mfma_f32_16x16x32_bf16 v[90:93], v[142:145], v[230:233], v[90:93]
	v_mfma_f32_16x16x32_bf16 v[78:81], v[130:133], v[234:237], v[78:81]
	v_mfma_f32_16x16x32_bf16 v[78:81], v[134:137], v[238:241], v[78:81]
	v_mfma_f32_16x16x32_bf16 v[74:77], v[138:141], v[234:237], v[74:77]
	v_mfma_f32_16x16x32_bf16 v[74:77], v[142:145], v[238:241], v[74:77]
	v_mfma_f32_16x16x32_bf16 v[118:121], v[170:173], v[210:213], v[118:121]
	v_mfma_f32_16x16x32_bf16 v[118:121], v[174:177], v[214:217], v[118:121]
	v_mfma_f32_16x16x32_bf16 v[114:117], v[202:205], v[210:213], v[114:117]
	v_mfma_f32_16x16x32_bf16 v[114:117], v[206:209], v[214:217], v[114:117]
	v_mfma_f32_16x16x32_bf16 v[102:105], v[170:173], v[218:221], v[102:105]
	v_mfma_f32_16x16x32_bf16 v[102:105], v[174:177], v[222:225], v[102:105]
	v_mfma_f32_16x16x32_bf16 v[98:101], v[202:205], v[218:221], v[98:101]
	v_mfma_f32_16x16x32_bf16 v[98:101], v[206:209], v[222:225], v[98:101]
	v_mfma_f32_16x16x32_bf16 v[86:89], v[170:173], v[226:229], v[86:89]
	v_mfma_f32_16x16x32_bf16 v[86:89], v[174:177], v[230:233], v[86:89]
	v_mfma_f32_16x16x32_bf16 v[82:85], v[202:205], v[226:229], v[82:85]
	v_mfma_f32_16x16x32_bf16 v[82:85], v[206:209], v[230:233], v[82:85]
	v_mfma_f32_16x16x32_bf16 v[70:73], v[170:173], v[234:237], v[70:73]
	v_mfma_f32_16x16x32_bf16 v[70:73], v[174:177], v[238:241], v[70:73]
	v_mfma_f32_16x16x32_bf16 v[66:69], v[202:205], v[234:237], v[66:69]
	v_mfma_f32_16x16x32_bf16 v[66:69], v[206:209], v[238:241], v[66:69]
	s_barrier
	s_setprio 0
	s_add_i32 s14, s43, s23
	v_lshl_add_u64 v[178:179], v[178:179], 0, s[94:95]
	s_mov_b32 m0, s14
	ds_read_b128 v[210:213], v201 offset:49152
	ds_read_b128 v[214:217], v201 offset:50176
	ds_read_b128 v[218:221], v201 offset:51200
	ds_read_b128 v[222:225], v201 offset:52224
	ds_read_b128 v[226:229], v201 offset:53248
	ds_read_b128 v[230:233], v201 offset:54272
	ds_read_b128 v[234:237], v201 offset:55296
	ds_read_b128 v[238:241], v201 offset:56320
	global_load_lds_dwordx4 v[178:179], off
	v_lshl_add_u64 v[178:179], v[242:243], 0, s[94:95]
	s_add_i32 m0, s14, 0x2000
	s_add_i32 s14, s75, s23
	global_load_lds_dwordx4 v[178:179], off
	v_lshl_add_u64 v[178:179], v[244:245], 0, s[94:95]
	s_mov_b32 m0, s14
	s_nop 0
	global_load_lds_dwordx4 v[178:179], off
	v_lshl_add_u64 v[178:179], v[246:247], 0, s[94:95]
	s_add_i32 m0, s14, 0x2000
	s_nop 0
	global_load_lds_dwordx4 v[178:179], off
	v_lshl_add_u64 v[178:179], v[248:249], 0, s[94:95]
	s_mov_b32 m0, s63
	s_nop 0
	global_load_lds_dwordx4 v[178:179], off
	v_lshl_add_u64 v[178:179], v[250:251], 0, s[94:95]
	s_mov_b32 m0, s70
	s_nop 0
	global_load_lds_dwordx4 v[178:179], off
	s_waitcnt vmcnt(8) lgkmcnt(0)
	s_setprio 1
	s_barrier
	v_mfma_f32_16x16x32_bf16 v[62:65], v[130:133], v[210:213], v[62:65]
	v_mfma_f32_16x16x32_bf16 v[62:65], v[134:137], v[214:217], v[62:65]
	v_mfma_f32_16x16x32_bf16 v[58:61], v[138:141], v[210:213], v[58:61]
	v_mfma_f32_16x16x32_bf16 v[58:61], v[142:145], v[214:217], v[58:61]
	v_mfma_f32_16x16x32_bf16 v[46:49], v[130:133], v[218:221], v[46:49]
	v_mfma_f32_16x16x32_bf16 v[46:49], v[134:137], v[222:225], v[46:49]
	v_mfma_f32_16x16x32_bf16 v[42:45], v[138:141], v[218:221], v[42:45]
	v_mfma_f32_16x16x32_bf16 v[42:45], v[142:145], v[222:225], v[42:45]
	v_mfma_f32_16x16x32_bf16 v[30:33], v[130:133], v[226:229], v[30:33]
	v_mfma_f32_16x16x32_bf16 v[30:33], v[134:137], v[230:233], v[30:33]
	v_mfma_f32_16x16x32_bf16 v[26:29], v[138:141], v[226:229], v[26:29]
	v_mfma_f32_16x16x32_bf16 v[26:29], v[142:145], v[230:233], v[26:29]
	v_mfma_f32_16x16x32_bf16 v[14:17], v[130:133], v[234:237], v[14:17]
	v_mfma_f32_16x16x32_bf16 v[14:17], v[134:137], v[238:241], v[14:17]
	v_mfma_f32_16x16x32_bf16 v[10:13], v[138:141], v[234:237], v[10:13]
	v_mfma_f32_16x16x32_bf16 v[10:13], v[142:145], v[238:241], v[10:13]
	v_mfma_f32_16x16x32_bf16 v[54:57], v[170:173], v[210:213], v[54:57]
	v_mfma_f32_16x16x32_bf16 v[54:57], v[174:177], v[214:217], v[54:57]
	v_mfma_f32_16x16x32_bf16 v[50:53], v[202:205], v[210:213], v[50:53]
	v_mfma_f32_16x16x32_bf16 v[50:53], v[206:209], v[214:217], v[50:53]
	v_mfma_f32_16x16x32_bf16 v[38:41], v[170:173], v[218:221], v[38:41]
	v_mfma_f32_16x16x32_bf16 v[38:41], v[174:177], v[222:225], v[38:41]
	v_mfma_f32_16x16x32_bf16 v[34:37], v[202:205], v[218:221], v[34:37]
	v_mfma_f32_16x16x32_bf16 v[34:37], v[206:209], v[222:225], v[34:37]
	v_mfma_f32_16x16x32_bf16 v[22:25], v[170:173], v[226:229], v[22:25]
	v_mfma_f32_16x16x32_bf16 v[22:25], v[174:177], v[230:233], v[22:25]
	v_mfma_f32_16x16x32_bf16 v[18:21], v[202:205], v[226:229], v[18:21]
	v_mfma_f32_16x16x32_bf16 v[18:21], v[206:209], v[230:233], v[18:21]
	v_mfma_f32_16x16x32_bf16 v[6:9], v[170:173], v[234:237], v[6:9]
	v_mfma_f32_16x16x32_bf16 v[6:9], v[174:177], v[238:241], v[6:9]
	v_mfma_f32_16x16x32_bf16 v[2:5], v[202:205], v[234:237], v[2:5]
	v_mfma_f32_16x16x32_bf16 v[2:5], v[206:209], v[238:241], v[2:5]
	s_barrier
	s_setprio 0
	s_add_u32 s12, s12, 0x100
	s_addc_u32 s13, s13, 0
	s_add_u32 s16, s16, 0x100
	s_addc_u32 s17, s17, 0
	s_cmp_ge_u32 s42, s28
	s_mov_b32 s14, s42
	s_cbranch_scc0 .LBB0_322
